# DSA attend softmax pass batched 8 slots per iteration (was 4)
# speedup vs baseline: 1.0062x; 1.0062x over previous
.LBB0_270:
	s_waitcnt vmcnt(0)
	v_and_b32_e32 v98, 64, v198
	v_xor_b32_e32 v2, 16, v198
	v_add_u32_e32 v14, 64, v98
	v_cmp_lt_i32_e32 vcc, v2, v14
	v_max_f32_e32 v3, v204, v204
	v_mov_b32_e32 v15, 0
	v_cndmask_b32_e32 v2, v198, v2, vcc
	v_lshlrev_b32_e32 v99, 2, v2
	ds_bpermute_b32 v2, v99, v204
	s_waitcnt lgkmcnt(0)
	v_max_f32_e32 v2, v2, v2
	v_max_f32_e32 v2, v3, v2
	v_xor_b32_e32 v3, 32, v198
	v_cmp_lt_i32_e32 vcc, v3, v14
	s_nop 1
	v_cndmask_b32_e32 v3, v198, v3, vcc
	v_lshlrev_b32_e32 v100, 2, v3
	ds_bpermute_b32 v3, v100, v2
	v_cmp_ge_u32_e32 vcc, s50, v182
	s_waitcnt lgkmcnt(0)
	v_max_f32_e32 v3, v3, v3
	v_max_f32_e32 v2, v2, v3
	v_or_b32_e32 v3, v98, v181
	v_lshlrev_b32_e32 v3, 2, v3
	ds_bpermute_b32 v2, v3, v2
	v_mov_b32_e32 v15, 0
	v_mov_b32_e32 v4, v182
	s_movk_i32 s42, 4
	s_waitcnt lgkmcnt(0)
	v_mov_b32_e32 v3, v203
.Ldsa_sm_loop:
	ds_read_b32 v208, v3
	ds_read_b32 v209, v3 offset:256
	ds_read_b32 v210, v3 offset:512
	ds_read_b32 v211, v3 offset:768
	ds_read_b32 v212, v3 offset:1024
	ds_read_b32 v213, v3 offset:1280
	ds_read_b32 v214, v3 offset:1536
	ds_read_b32 v215, v3 offset:1792
	s_waitcnt lgkmcnt(0)
	v_sub_f32_e32 v208, v208, v2
	v_sub_f32_e32 v209, v209, v2
	v_sub_f32_e32 v210, v210, v2
	v_sub_f32_e32 v211, v211, v2
	v_sub_f32_e32 v212, v212, v2
	v_sub_f32_e32 v213, v213, v2
	v_sub_f32_e32 v214, v214, v2
	v_sub_f32_e32 v215, v215, v2
	v_mul_f32_e32 v208, 0x3fb8aa3b, v208
	v_mul_f32_e32 v209, 0x3fb8aa3b, v209
	v_mul_f32_e32 v210, 0x3fb8aa3b, v210
	v_mul_f32_e32 v211, 0x3fb8aa3b, v211
	v_mul_f32_e32 v212, 0x3fb8aa3b, v212
	v_mul_f32_e32 v213, 0x3fb8aa3b, v213
	v_mul_f32_e32 v214, 0x3fb8aa3b, v214
	v_mul_f32_e32 v215, 0x3fb8aa3b, v215
	v_exp_f32_e32 v208, v208
	v_exp_f32_e32 v209, v209
	v_exp_f32_e32 v210, v210
	v_exp_f32_e32 v211, v211
	v_exp_f32_e32 v212, v212
	v_exp_f32_e32 v213, v213
	v_exp_f32_e32 v214, v214
	v_exp_f32_e32 v215, v215
	v_add_u32_e32 v217, 8, v4
	v_add_u32_e32 v218, 16, v4
	v_add_u32_e32 v219, 24, v4
	v_add_u32_e32 v220, 32, v4
	v_add_u32_e32 v221, 40, v4
	v_add_u32_e32 v222, 48, v4
	v_add_u32_e32 v223, 56, v4
	ds_write_b32 v3, v208
	ds_write_b32 v3, v209 offset:256
	ds_write_b32 v3, v210 offset:512
	ds_write_b32 v3, v211 offset:768
	ds_write_b32 v3, v212 offset:1024
	ds_write_b32 v3, v213 offset:1280
	ds_write_b32 v3, v214 offset:1536
	ds_write_b32 v3, v215 offset:1792
	v_cmp_ge_u32_e32 vcc, s50, v4
	s_nop 1
	v_cndmask_b32_e32 v12, 0, v208, vcc
	v_add_f32_e32 v15, v15, v12
	v_cmp_ge_u32_e32 vcc, s50, v217
	s_nop 1
	v_cndmask_b32_e32 v12, 0, v209, vcc
	v_add_f32_e32 v15, v15, v12
	v_cmp_ge_u32_e32 vcc, s50, v218
	s_nop 1
	v_cndmask_b32_e32 v12, 0, v210, vcc
	v_add_f32_e32 v15, v15, v12
	v_cmp_ge_u32_e32 vcc, s50, v219
	s_nop 1
	v_cndmask_b32_e32 v12, 0, v211, vcc
	v_add_f32_e32 v15, v15, v12
	v_cmp_ge_u32_e32 vcc, s50, v220
	s_nop 1
	v_cndmask_b32_e32 v12, 0, v212, vcc
	v_add_f32_e32 v15, v15, v12
	v_cmp_ge_u32_e32 vcc, s50, v221
	s_nop 1
	v_cndmask_b32_e32 v12, 0, v213, vcc
	v_add_f32_e32 v15, v15, v12
	v_cmp_ge_u32_e32 vcc, s50, v222
	s_nop 1
	v_cndmask_b32_e32 v12, 0, v214, vcc
	v_add_f32_e32 v15, v15, v12
	v_cmp_ge_u32_e32 vcc, s50, v223
	s_nop 1
	v_cndmask_b32_e32 v12, 0, v215, vcc
	v_add_f32_e32 v15, v15, v12
	v_add_u32_e32 v4, 64, v4
	v_add_u32_e32 v3, 0x800, v3
	s_sub_u32 s42, s42, 1
	s_cmp_lg_u32 s42, 0
	s_cbranch_scc1 .Ldsa_sm_loop
